# XCD-local barrier at the FF1-to-FF2 seam (row panels are XCD-owned in both GEMMs): no L2 write-back and no top-level hop there
# speedup vs baseline: 1.0076x; 1.0076x over previous
.LBB0_1061:
	s_andn2_saveexec_b64 s[4:5], s[10:11]
	s_cbranch_execz .LBB0_1081
	s_mov_b64 s[10:11], exec
	buffer_inv sc1
	s_branch .Lmy_xl_rel
	s_waitcnt lgkmcnt(0)
	s_waitcnt vmcnt(0)
	v_mbcnt_lo_u32_b32 v3, s10, 0
	v_mbcnt_hi_u32_b32 v3, s11, v3
	v_cmp_eq_u32_e32 vcc, 0, v3
	s_and_saveexec_b64 s[14:15], vcc
	s_cbranch_execz .LBB0_1064
	s_bcnt1_i32_b64 s4, s[10:11]
	v_mov_b32_e32 v4, s4
	v_readlane_b32 s4, v253, 42
	v_readlane_b32 s5, v253, 43
	s_nop 4
	global_atomic_add v4, v99, v4, s[4:5] sc0

.Lmy_xl_rel:
	s_mov_b64 s[10:11], exec
	v_mbcnt_lo_u32_b32 v2, s10, 0
	v_mbcnt_hi_u32_b32 v2, s11, v2
	v_cmp_eq_u32_e32 vcc, 0, v2
	s_waitcnt vmcnt(0)
	s_nop 0
	s_and_saveexec_b64 s[14:15], vcc
	s_cbranch_execz .LBB0_1080
	s_bcnt1_i32_b64 s4, s[10:11]
	v_mov_b32_e32 v2, s4
	v_readlane_b32 s4, v253, 40
	v_readlane_b32 s5, v253, 41
	s_nop 4
	global_atomic_add v99, v2, s[4:5]
